# IN0/IN1 (EpiScale): same hoisted-rss + LDS rstd table + exact-intent first-iteration vmcnt as GU
# baseline (speedup 1.0000x reference)
; #define LAS __attribute__((address_space(3)))
; #define PG8_STAGE(bufoff, gbase, voff) do { _Pragma("unroll") for (int _i = 0; _i < 2; ++_i) \
;         __builtin_amdgcn_global_load_lds((const unsigned*)((const char*)(gbase) + (voff)[_i]), (LAS unsigned*)(lds + (bufoff) + ldsw + _i * 8192), 16, 0, 0); } while (0)
; #define PG8_WAIT_V(n) asm volatile("s_waitcnt vmcnt(" #n ")" ::: "memory")
; #define PG8_BAR __builtin_amdgcn_s_barrier()
; template <class Epi>
; DI void gemm_phase(LAS unsigned char* lds, const int tid, const Gemm g, const StaticOrder& S, const Epi& E) {
;     const int wid = __builtin_amdgcn_readfirstlane(tid >> 6), lane = tid & 63, wr = wid >> 2, wc = wid & 3, fr = lane & 15, fq = lane >> 4;
;     const int K = g.K, nt = K / BK, lda = g.lda;
;     unsigned voffA[2], voffB[2];
; #pragma unroll
;     for (int i = 0; i < 2; ++i) { int R, C; stage_rc(tid * 16 + i * 8192, R, C); const int Rb = (R & ~31) + perm32(R & 31);
;         voffA[i] = (unsigned)(R * lda + C) * 2u; voffB[i] = (unsigned)(Rb * K + C) * 2u; }
;     const size_t kstep = (size_t)(BK * 2);
;     const size_t hstepA = (size_t)HALF * lda * 2, hstepB = (size_t)HALF * K * 2;
;     const size_t tstepA = 2 * hstepA, tstepB = 2 * hstepB;
;     const unsigned ldsw = (unsigned)wid * 1024u;
;     const int aoff = lds_byte(wr * 64 + fr, fq * 8), boff = lds_byte(wc * 32 + fr, fq * 8);
;     ...
;     Unit cur, nxt; int ui = 0;
;     if (!S.next(0, cur)) return;
;     f32x4 acc[2][2][4][2];
; #pragma unroll
;     for (int a = 0; a < 2; ++a)
; #pragma unroll
;         for (int b = 0; b < 2; ++b)
; #pragma unroll
;             for (int m = 0; m < 4; ++m)
; #pragma unroll
;                 for (int n = 0; n < 2; ++n) acc[a][b][m][n] = (f32x4){0.f, 0.f, 0.f, 0.f};
;     bf16x8 At[4][2], B0[2][2], B1[2][2];
;     const char* cA = (const char*)g.A + (size_t)cur.pm * tstepA; const char* cB = (const char*)g.Bt + (size_t)cur.pn * tstepB;
;     PG8_STAGE(PG8_SB(0, 0), cB, voffB); PG8_STAGE(PG8_SB(0, 1), cB + hstepB, voffB); PG8_STAGE(PG8_SA(0, 0), cA, voffA); PG8_STAGE(PG8_SA(0, 1), cA + hstepA, voffA);
;     if (wr == 1) PG8_BAR;
;     PG8_WAIT_V(2); PG8_BAR;
;     PG8_STAGE(PG8_SB(1, 0), cB + kstep, voffB); PG8_STAGE(PG8_SA(1, 0), cA + kstep, voffA); PG8_STAGE(PG8_SB(1, 1), cB + hstepB + kstep, voffB);
;     PG8_WAIT_V(6); PG8_BAR;
.LBB0_414:
	v_readlane_b32 s0, v255, 3
	v_readlane_b32 s1, v255, 4
	s_and_b64 s[26:27], s[0:1], exec
	s_movk_i32 s7, 0x900
	s_cselect_b32 s65, 0xb00, s7
	s_lshl_b32 s7, s11, 5
	s_and_b32 s37, s7, 0x60
	s_add_i32 m0, s42, 0x18000
	v_lshl_add_u64 v[8:9], v[8:9], 0, s[54:55]
	s_lshl_b32 s36, s10, 13
	s_lshl_b32 s11, s37, 7
	s_waitcnt vmcnt(2)
	s_barrier
	global_load_lds_dwordx4 v[8:9], off
	v_lshl_add_u64 v[6:7], v[6:7], 0, s[54:55]
	s_add_i32 m0, s42, 0x1a000
	s_add_i32 s66, s42, 0x8000
	s_add_i32 s67, s42, 0xa000
	global_load_lds_dwordx4 v[6:7], off
	v_lshl_add_u64 v[2:3], v[2:3], 0, s[54:55]
	s_mov_b32 m0, s66
	s_add_u32 s26, s60, 0x40080
	global_load_lds_dwordx4 v[2:3], off
	v_lshl_add_u64 v[2:3], v[4:5], 0, s[54:55]
	s_mov_b32 m0, s67
	s_addc_u32 s27, s61, 0
	global_load_lds_dwordx4 v[2:3], off
	s_add_i32 m0, s42, 0x1c000
	v_lshl_add_u64 v[2:3], s[26:27], 0, v[0:1]
	global_load_lds_dwordx4 v[2:3], off
	v_lshl_add_u64 v[2:3], s[26:27], 0, v[130:131]
	s_add_i32 m0, s42, 0x1e000
	v_and_b32_e32 v145, 15, v10
	global_load_lds_dwordx4 v[2:3], off
	v_bfe_u32 v3, v10, 4, 2
	v_lshlrev_b32_e32 v4, 4, v3
	v_lshlrev_b32_e32 v5, 2, v10
	v_lshrrev_b32_e32 v2, 4, v10
	v_lshl_or_b32 v4, v145, 6, v4
	v_and_b32_e32 v5, 32, v5
	v_bitop3_b32 v6, v4, s36, v5 bitop3:0xde
	v_bitop3_b32 v147, s11, v4, v5 bitop3:0xf6
	v_lshlrev_b32_e32 v4, 5, v3
	v_lshlrev_b32_e32 v2, 6, v2
	s_movk_i32 s0, 0xa0
	v_bitop3_b32 v148, v2, s0, v4 bitop3:0xc8
	v_lshlrev_b32_e32 v2, 14, v15
	v_and_b32_e32 v2, 0xffff8000, v2
	v_lshl_or_b32 v149, v3, 3, s37
	v_lshl_add_u32 v2, v14, 11, v2
	v_and_b32_e32 v3, 1, v15
	v_lshl_or_b32 v2, v3, 6, v2
	v_lshl_add_u32 v136, v16, 1, v2
	v_lshlrev_b32_e32 v2, 14, v11
	v_and_b32_e32 v2, 0xffff8000, v2
	s_waitcnt vmcnt(6)
	v_lshl_add_u32 v2, v12, 11, v2
	v_and_b32_e32 v3, 1, v11
	s_cmpk_lt_u32 s5, 0x100
	v_lshl_or_b32 v2, v3, 6, v2
	s_sext_i32_i8 s7, s4
	s_mov_b32 s72, 0
	v_lshl_or_b32 v146, s10, 6, v145
	s_cselect_b64 s[10:11], -1, 0
	s_ashr_i32 s73, s14, 31
	v_mov_b32_e32 v137, v1
	v_lshl_add_u32 v138, v13, 1, v2
	v_mov_b32_e32 v139, v1
	v_add_u32_e32 v150, 0, v6
	s_barrier
	v_lshrrev_b32_e32 v2, 8, v240
	v_bfe_u32 v3, v240, 6, 2
	v_bfe_u32 v4, v240, 5, 1
	v_bfe_u32 v5, v240, 1, 4
	v_lshlrev_b32_e32 v252, 6, v2
	v_lshrrev_b32_e32 v251, 1, v3
	v_lshl_add_u32 v252, v251, 7, v252
	v_and_b32_e32 v251, 1, v3
	v_lshl_add_u32 v252, v251, 5, v252
	v_lshl_add_u32 v252, v4, 4, v252
	v_add_u32_e32 v252, v252, v5
	v_and_b32_e32 v251, 1, v240
	v_lshlrev_b32_e32 v252, 6, v252
	v_lshl_add_u32 v252, v251, 5, v252
	v_lshl_add_u32 v251, v3, 1, v4
	v_lshlrev_b32_e32 v251, 2, v251
	v_lshl_add_u32 v251, v5, 5, v251
	v_lshl_add_u32 v251, v2, 11, v251
	v_add_u32_e32 v251, 0x20000, v251
	s_branch .LBB0_417

; DI float rss_sum(const float* rss, int row) {
;     const f32x4* p = (const f32x4*)(rss + (size_t)row * 16); const f32x4 a = p[0], b = p[1], c = p[2], d = p[3];
;     return (((a.x + a.y) + (a.z + a.w)) + ((b.x + b.y) + (b.z + b.w))) + (((c.x + c.y) + (c.z + c.w)) + ((d.x + d.y) + (d.z + d.w))); }
; template <class Epi>
; DI void gemm_phase(LAS unsigned char* lds, const int tid, const Gemm g, const StaticOrder& S, const Epi& E) {
;     ...
;     for (;;) {
;         const bool has_next = S.next(ui + 1, nxt);
;         const char* nA = has_next ? (const char*)g.A + (size_t)nxt.pm * tstepA : cA; const char* nB = has_next ? (const char*)g.Bt + (size_t)nxt.pn * tstepB : cB;
.LBB0_419:
	s_cmp_lg_u32 s72, 1
	s_cselect_b32 s100, 1, 0
	s_cbranch_scc1 .Lin_noR0
	v_readlane_b32 s26, v253, 49
	s_lshl_b32 s27, s6, 14
	s_nop 1
	s_add_u32 s26, s26, s27
	v_readlane_b32 s27, v253, 50
	s_nop 1
	s_addc_u32 s27, s27, 0
	s_nop 4
	global_load_dwordx4 v[228:231], v252, s[26:27]
	global_load_dwordx2 v[232:233], v252, s[26:27] offset:16
	global_load_dwordx2 v[238:239], v252, s[26:27] offset:24

; #define PG8_STAGE(bufoff, gbase, voff) do { _Pragma("unroll") for (int _i = 0; _i < 2; ++_i) \
;         __builtin_amdgcn_global_load_lds((const unsigned*)((const char*)(gbase) + (voff)[_i]), (LAS unsigned*)(lds + (bufoff) + ldsw + _i * 8192), 16, 0, 0); } while (0)
; #define PG8_LDA(dst, b, h) do { _Pragma("unroll") for (int m = 0; m < 4; ++m) _Pragma("unroll") for (int k = 0; k < 2; ++k) dst[m][k] = *(const LAS bf16x8*)(lds + PG8_SA(b, h) + aoff + m * 2048 + k * 1024); } while (0)
; #define PG8_LDB(dst, b, h) do { _Pragma("unroll") for (int n = 0; n < 2; ++n) _Pragma("unroll") for (int k = 0; k < 2; ++k) dst[n][k] = *(const LAS bf16x8*)(lds + PG8_SB(b, h) + boff + n * 2048 + k * 1024); } while (0)
; #define PG8_MMA(ai, bj, At, Bt) do { __builtin_amdgcn_s_setprio(1); _Pragma("unroll") for (int m = 0; m < 4; ++m) _Pragma("unroll") for (int n = 0; n < 2; ++n) _Pragma("unroll") for (int k = 0; k < 2; ++k) \
;         acc[ai][bj][m][n] = __builtin_amdgcn_mfma_f32_16x16x32_bf16(Bt[n][k], At[m][k], acc[ai][bj][m][n], 0, 0, 0); __builtin_amdgcn_s_setprio(0); } while (0)
; #define PG8_WAIT_V(n) asm volatile("s_waitcnt vmcnt(" #n ")" ::: "memory")
; #define PG8_WAIT_L(n) asm volatile("s_waitcnt lgkmcnt(" #n ")" ::: "memory")
; DI float rss_sum(const float* rss, int row) {
;     const f32x4* p = (const f32x4*)(rss + (size_t)row * 16); const f32x4 a = p[0], b = p[1], c = p[2], d = p[3];
;     return (((a.x + a.y) + (a.z + a.w)) + ((b.x + b.y) + (b.z + b.w))) + (((c.x + c.y) + (c.z + c.w)) + ((d.x + d.y) + (d.z + d.w))); }
; DI void row_rstd8(const float* rss, int row0, int lane, int fq, float (&rs)[8]) {
;     float v[2];
; #pragma unroll
;     for (int e = 0; e < 2; ++e) { const int p = 2 * fq + e; const int row = row0 + (p >> 2) * 128 + (p & 3) * 16; v[e] = 1.0f / sqrtf(rss_sum(rss, row) * (1.0f / DM) + EPS); }
; template <class Epi>
; DI void gemm_phase(LAS unsigned char* lds, const int tid, const Gemm g, const StaticOrder& S, const Epi& E) {
;     ...
;             PG8_LDB(B0, 0, 0); PG8_LDB(B1, 0, 1); PG8_SCHED; PG8_LDA(At, 0, 0); PG8_STAGE(PG8_SA(1, 1), a1 + hstepA, voffA);
;             PG8_WAIT_V(8); PG8_WAIT_L(0); PG8_BAR; PG8_MMA(0, 0, At, B0); PG8_MMA(0, 1, At, B1); PG8_BAR; PG8_SCHED;
;             PG8_LDA(At, 0, 1); PG8_STAGE(PG8_SB(0, 0), b2, voffB); PG8_STAGE(PG8_SB(0, 1), b2 + hstepB, voffB); PG8_STAGE(PG8_SA(0, 0), a2, voffA);
.LBB0_420:
	s_cmp_eq_u32 s82, 0
	s_cbranch_scc0 .Lin_rs_skip
	s_waitcnt vmcnt(8)
	v_add_f32_e32 v152, v228, v229
	v_add_f32_e32 v153, v230, v231
	v_add_f32_e32 v154, v232, v233
	v_add_f32_e32 v155, v238, v239
	v_add_f32_e32 v152, v152, v153
	v_add_f32_e32 v154, v154, v155
	v_add_f32_e32 v152, v152, v154
	s_nop 1
	v_mov_b32_dpp v153, v152 quad_perm:[1,0,3,2] row_mask:0xf bank_mask:0xf
	s_nop 0
	v_add_f32_e32 v152, v152, v153
	v_fmamk_f32 v152, v152, 0x3a800000, v241
	v_cmp_gt_f32_e32 vcc, s3, v152
	v_mul_f32_e32 v153, 0x4f800000, v152
	s_nop 1
	v_cndmask_b32_e32 v152, v152, v153, vcc
	v_sqrt_f32_e32 v153, v152
	s_nop 0
	v_add_u32_e32 v154, -1, v153
	v_fma_f32 v155, -v154, v153, v152
	v_cmp_ge_f32_e64 s[26:27], 0, v155
	v_add_u32_e32 v155, 1, v153
	s_nop 1
	v_cndmask_b32_e64 v154, v153, v154, s[26:27]
	v_fma_f32 v153, -v155, v153, v152
	v_cmp_lt_f32_e64 s[26:27], 0, v153
	s_nop 1
	v_cndmask_b32_e64 v153, v154, v155, s[26:27]
	v_mul_f32_e32 v154, 0x37800000, v153
	v_cndmask_b32_e32 v153, v153, v154, vcc
	v_cmp_class_f32_e32 vcc, v152, v242
	s_nop 1
	v_cndmask_b32_e32 v152, v153, v152, vcc
	v_div_scale_f32 v153, s[26:27], v152, v152, 1.0
	v_rcp_f32_e32 v154, v153
	s_nop 0
	v_fma_f32 v155, -v153, v154, 1.0
	v_fmac_f32_e32 v154, v155, v154
	v_div_scale_f32 v155, vcc, 1.0, v152, 1.0
	v_mul_f32_e32 v156, v155, v154
	v_fma_f32 v157, -v153, v156, v155
	v_fmac_f32_e32 v156, v157, v154
	v_fma_f32 v153, -v153, v156, v155
	s_nop 0
	v_div_fmas_f32 v153, v153, v154, v156
	v_div_fixup_f32 v152, v153, v152, 1.0
	ds_write_b32 v251, v152
.Lin_rs_skip:
	s_add_u32 s26, s58, 0xfffc0080
	s_addc_u32 s27, s59, -1
	s_add_i32 s83, 0, 0x10000
	s_cmp_eq_u32 s82, 12
	s_cselect_b32 s63, s49, s27
	s_cselect_b32 s62, s78, s26
	v_add_u32_e32 v144, s83, v147
	s_cselect_b32 s61, s37, s81
	s_cselect_b32 s60, s79, s80
	s_add_i32 s84, 0, 0x14000
	ds_read_b128 v[140:143], v144
	ds_read_b128 v[152:155], v144 offset:1024
	ds_read_b128 v[156:159], v144 offset:2048
	ds_read_b128 v[160:163], v144 offset:3072
	v_add_u32_e32 v144, s84, v147
	ds_read_b128 v[164:167], v144
	ds_read_b128 v[168:171], v144 offset:1024
	ds_read_b128 v[172:175], v144 offset:2048
	ds_read_b128 v[176:179], v144 offset:3072
	v_lshl_add_u64 v[204:205], s[58:59], 0, v[136:137]
	s_add_i32 m0, s42, 0xc000
	ds_read_b128 v[180:183], v150
	ds_read_b128 v[184:187], v150 offset:1024
	ds_read_b128 v[188:191], v150 offset:2048
	ds_read_b128 v[192:195], v150 offset:3072
	ds_read_b128 v[196:199], v150 offset:4096
	ds_read_b128 v[200:203], v150 offset:5120
	ds_read_b128 v[208:211], v150 offset:6144
	ds_read_b128 v[212:215], v150 offset:7168
	global_load_lds_dwordx4 v[204:205], off
	v_lshl_add_u64 v[204:205], s[58:59], 0, v[138:139]
	s_add_i32 m0, s42, 0xe000
	s_nop 0
	global_load_lds_dwordx4 v[204:205], off
	s_cmp_eq_u32 s100, 0
	s_cbranch_scc1 .Lin_ws1
	s_waitcnt vmcnt(27)
	s_branch .Lin_wd1

; #define PG8_STAGE(bufoff, gbase, voff) do { _Pragma("unroll") for (int _i = 0; _i < 2; ++_i) \
;         __builtin_amdgcn_global_load_lds((const unsigned*)((const char*)(gbase) + (voff)[_i]), (LAS unsigned*)(lds + (bufoff) + ldsw + _i * 8192), 16, 0, 0); } while (0)
; #define PG8_LDA(dst, b, h) do { _Pragma("unroll") for (int m = 0; m < 4; ++m) _Pragma("unroll") for (int k = 0; k < 2; ++k) dst[m][k] = *(const LAS bf16x8*)(lds + PG8_SA(b, h) + aoff + m * 2048 + k * 1024); } while (0)
; #define PG8_MMA(ai, bj, At, Bt) do { __builtin_amdgcn_s_setprio(1); _Pragma("unroll") for (int m = 0; m < 4; ++m) _Pragma("unroll") for (int n = 0; n < 2; ++n) _Pragma("unroll") for (int k = 0; k < 2; ++k) \
;         acc[ai][bj][m][n] = __builtin_amdgcn_mfma_f32_16x16x32_bf16(Bt[n][k], At[m][k], acc[ai][bj][m][n], 0, 0, 0); __builtin_amdgcn_s_setprio(0); } while (0)
; #define PG8_WAIT_V(n) asm volatile("s_waitcnt vmcnt(" #n ")" ::: "memory")
; #define PG8_WAIT_L(n) asm volatile("s_waitcnt lgkmcnt(" #n ")" ::: "memory")
; #define PG8_BAR __builtin_amdgcn_s_barrier()
; #define PG8_SCHED __builtin_amdgcn_sched_barrier(0)
; template <class Epi>
; DI void gemm_phase(LAS unsigned char* lds, const int tid, const Gemm g, const StaticOrder& S, const Epi& E) {
;     ...
;             PG8_WAIT_V(8); PG8_WAIT_L(0); PG8_BAR; PG8_MMA(0, 0, At, B0); PG8_MMA(0, 1, At, B1); PG8_BAR; PG8_SCHED;
;             PG8_LDA(At, 0, 1); PG8_STAGE(PG8_SB(0, 0), b2, voffB); PG8_STAGE(PG8_SB(0, 1), b2 + hstepB, voffB); PG8_STAGE(PG8_SA(0, 0), a2, voffA);
;             PG8_WAIT_V(8); PG8_WAIT_L(0); PG8_BAR; PG8_MMA(1, 0, At, B0); PG8_MMA(1, 1, At, B1); PG8_BAR; PG8_SCHED;
.Lin_wd1:
	s_waitcnt lgkmcnt(0)
	s_barrier
	s_setprio 1
	s_waitcnt lgkmcnt(0)
	v_mfma_f32_16x16x32_bf16 v[126:129], v[140:143], v[180:183], v[126:129]
	v_mfma_f32_16x16x32_bf16 v[122:125], v[156:159], v[180:183], v[122:125]
	v_mfma_f32_16x16x32_bf16 v[118:121], v[140:143], v[188:191], v[118:121]
	v_mfma_f32_16x16x32_bf16 v[110:113], v[156:159], v[188:191], v[110:113]
	v_mfma_f32_16x16x32_bf16 v[102:105], v[140:143], v[196:199], v[102:105]
	v_mfma_f32_16x16x32_bf16 v[94:97], v[156:159], v[196:199], v[94:97]
	v_mfma_f32_16x16x32_bf16 v[86:89], v[140:143], v[208:211], v[86:89]
	v_mfma_f32_16x16x32_bf16 v[78:81], v[156:159], v[208:211], v[78:81]
	v_mfma_f32_16x16x32_bf16 v[126:129], v[152:155], v[184:187], v[126:129]
	v_mfma_f32_16x16x32_bf16 v[122:125], v[160:163], v[184:187], v[122:125]
	v_mfma_f32_16x16x32_bf16 v[118:121], v[152:155], v[192:195], v[118:121]
	v_mfma_f32_16x16x32_bf16 v[110:113], v[160:163], v[192:195], v[110:113]
	v_mfma_f32_16x16x32_bf16 v[102:105], v[152:155], v[200:203], v[102:105]
	v_mfma_f32_16x16x32_bf16 v[94:97], v[160:163], v[200:203], v[94:97]
	v_mfma_f32_16x16x32_bf16 v[86:89], v[152:155], v[212:215], v[86:89]
	v_mfma_f32_16x16x32_bf16 v[78:81], v[160:163], v[212:215], v[78:81]
	s_setprio 0
	s_setprio 1
	v_mfma_f32_16x16x32_bf16 v[114:117], v[164:167], v[180:183], v[114:117]
	v_mfma_f32_16x16x32_bf16 v[106:109], v[172:175], v[180:183], v[106:109]
	v_mfma_f32_16x16x32_bf16 v[98:101], v[164:167], v[188:191], v[98:101]
	v_mfma_f32_16x16x32_bf16 v[90:93], v[172:175], v[188:191], v[90:93]
	v_mfma_f32_16x16x32_bf16 v[82:85], v[164:167], v[196:199], v[82:85]
	v_mfma_f32_16x16x32_bf16 v[74:77], v[172:175], v[196:199], v[74:77]
	v_mfma_f32_16x16x32_bf16 v[70:73], v[164:167], v[208:211], v[70:73]
	v_mfma_f32_16x16x32_bf16 v[66:69], v[172:175], v[208:211], v[66:69]
	v_mfma_f32_16x16x32_bf16 v[114:117], v[168:171], v[184:187], v[114:117]
	v_mfma_f32_16x16x32_bf16 v[106:109], v[176:179], v[184:187], v[106:109]
	v_mfma_f32_16x16x32_bf16 v[98:101], v[168:171], v[192:195], v[98:101]
	v_mfma_f32_16x16x32_bf16 v[90:93], v[176:179], v[192:195], v[90:93]
	v_mfma_f32_16x16x32_bf16 v[82:85], v[168:171], v[200:203], v[82:85]
	v_mfma_f32_16x16x32_bf16 v[74:77], v[176:179], v[200:203], v[74:77]
	v_mfma_f32_16x16x32_bf16 v[70:73], v[168:171], v[212:215], v[70:73]
	v_mfma_f32_16x16x32_bf16 v[66:69], v[176:179], v[212:215], v[66:69]
	s_setprio 0
	s_barrier
	s_add_i32 s26, s83, s30
	v_lshl_add_u64 v[204:205], s[60:61], 0, v[0:1]
	s_mov_b32 m0, s26
	ds_read_b128 v[180:183], v150 offset:16384
	ds_read_b128 v[184:187], v150 offset:17408
	ds_read_b128 v[188:191], v150 offset:18432
	ds_read_b128 v[192:195], v150 offset:19456
	ds_read_b128 v[196:199], v150 offset:20480
	ds_read_b128 v[200:203], v150 offset:21504
	ds_read_b128 v[208:211], v150 offset:22528
	ds_read_b128 v[212:215], v150 offset:23552
	global_load_lds_dwordx4 v[204:205], off
	s_add_i32 m0, s26, 0x2000
	s_add_u32 s26, s60, 0x40000
	v_lshl_add_u64 v[216:217], s[60:61], 0, v[130:131]
	s_addc_u32 s27, s61, 0
	s_add_i32 s83, s84, s30
	global_load_lds_dwordx4 v[216:217], off
	v_lshl_add_u64 v[218:219], s[26:27], 0, v[0:1]
	s_mov_b32 m0, s83
	v_lshl_add_u64 v[220:221], s[62:63], 0, v[132:133]
	global_load_lds_dwordx4 v[218:219], off
	v_lshl_add_u64 v[218:219], s[26:27], 0, v[130:131]
	s_add_i32 m0, s83, 0x2000
	s_nop 0
	global_load_lds_dwordx4 v[218:219], off
	v_lshl_add_u64 v[218:219], s[62:63], 0, v[134:135]
	s_mov_b32 m0, s42
	s_nop 0
	global_load_lds_dwordx4 v[218:219], off
	s_mov_b32 m0, s43
	s_nop 0
	global_load_lds_dwordx4 v[220:221], off
	s_cmp_eq_u32 s100, 0
	s_cbranch_scc1 .Lin_ws2
	s_waitcnt vmcnt(27)
	s_mov_b32 s100, 0
	s_branch .Lin_wd2

; #define PG8_STAGE(bufoff, gbase, voff) do { _Pragma("unroll") for (int _i = 0; _i < 2; ++_i) \
;         __builtin_amdgcn_global_load_lds((const unsigned*)((const char*)(gbase) + (voff)[_i]), (LAS unsigned*)(lds + (bufoff) + ldsw + _i * 8192), 16, 0, 0); } while (0)
; #define PG8_LDA(dst, b, h) do { _Pragma("unroll") for (int m = 0; m < 4; ++m) _Pragma("unroll") for (int k = 0; k < 2; ++k) dst[m][k] = *(const LAS bf16x8*)(lds + PG8_SA(b, h) + aoff + m * 2048 + k * 1024); } while (0)
; #define PG8_LDB(dst, b, h) do { _Pragma("unroll") for (int n = 0; n < 2; ++n) _Pragma("unroll") for (int k = 0; k < 2; ++k) dst[n][k] = *(const LAS bf16x8*)(lds + PG8_SB(b, h) + boff + n * 2048 + k * 1024); } while (0)
; #define PG8_MMA(ai, bj, At, Bt) do { __builtin_amdgcn_s_setprio(1); _Pragma("unroll") for (int m = 0; m < 4; ++m) _Pragma("unroll") for (int n = 0; n < 2; ++n) _Pragma("unroll") for (int k = 0; k < 2; ++k) \
;         acc[ai][bj][m][n] = __builtin_amdgcn_mfma_f32_16x16x32_bf16(Bt[n][k], At[m][k], acc[ai][bj][m][n], 0, 0, 0); __builtin_amdgcn_s_setprio(0); } while (0)
; #define PG8_WAIT_V(n) asm volatile("s_waitcnt vmcnt(" #n ")" ::: "memory")
; #define PG8_WAIT_L(n) asm volatile("s_waitcnt lgkmcnt(" #n ")" ::: "memory")
; #define PG8_BAR __builtin_amdgcn_s_barrier()
; #define PG8_SCHED __builtin_amdgcn_sched_barrier(0)
; template <class Epi>
; DI void gemm_phase(LAS unsigned char* lds, const int tid, const Gemm g, const StaticOrder& S, const Epi& E) {
;     ...
;             PG8_WAIT_V(8); PG8_WAIT_L(0); PG8_BAR; PG8_MMA(1, 0, At, B0); PG8_MMA(1, 1, At, B1); PG8_BAR; PG8_SCHED;
;             PG8_LDB(B0, 1, 0); PG8_LDB(B1, 1, 1); PG8_SCHED; PG8_LDA(At, 1, 0); PG8_STAGE(PG8_SA(0, 1), a2 + hstepA, voffA);
;             PG8_WAIT_V(8); PG8_WAIT_L(0); PG8_BAR; PG8_MMA(0, 0, At, B0); PG8_MMA(0, 1, At, B1); PG8_BAR; PG8_SCHED;
.Lin_wd2:
	s_waitcnt lgkmcnt(0)
	s_barrier
	s_setprio 1
	s_waitcnt lgkmcnt(0)
	v_mfma_f32_16x16x32_bf16 v[62:65], v[140:143], v[180:183], v[62:65]
	v_mfma_f32_16x16x32_bf16 v[58:61], v[156:159], v[180:183], v[58:61]
	v_mfma_f32_16x16x32_bf16 v[54:57], v[140:143], v[188:191], v[54:57]
	v_mfma_f32_16x16x32_bf16 v[46:49], v[156:159], v[188:191], v[46:49]
	v_mfma_f32_16x16x32_bf16 v[38:41], v[140:143], v[196:199], v[38:41]
	v_mfma_f32_16x16x32_bf16 v[30:33], v[156:159], v[196:199], v[30:33]
	v_mfma_f32_16x16x32_bf16 v[22:25], v[140:143], v[208:211], v[22:25]
	v_mfma_f32_16x16x32_bf16 v[14:17], v[156:159], v[208:211], v[14:17]
	v_mfma_f32_16x16x32_bf16 v[62:65], v[152:155], v[184:187], v[62:65]
	v_mfma_f32_16x16x32_bf16 v[58:61], v[160:163], v[184:187], v[58:61]
	v_mfma_f32_16x16x32_bf16 v[54:57], v[152:155], v[192:195], v[54:57]
	v_mfma_f32_16x16x32_bf16 v[46:49], v[160:163], v[192:195], v[46:49]
	v_mfma_f32_16x16x32_bf16 v[38:41], v[152:155], v[200:203], v[38:41]
	v_mfma_f32_16x16x32_bf16 v[30:33], v[160:163], v[200:203], v[30:33]
	v_mfma_f32_16x16x32_bf16 v[22:25], v[152:155], v[212:215], v[22:25]
	v_mfma_f32_16x16x32_bf16 v[14:17], v[160:163], v[212:215], v[14:17]
	s_setprio 0
	s_setprio 1
	v_mfma_f32_16x16x32_bf16 v[50:53], v[164:167], v[180:183], v[50:53]
	v_mfma_f32_16x16x32_bf16 v[42:45], v[172:175], v[180:183], v[42:45]
	v_mfma_f32_16x16x32_bf16 v[34:37], v[164:167], v[188:191], v[34:37]
	v_mfma_f32_16x16x32_bf16 v[26:29], v[172:175], v[188:191], v[26:29]
	v_mfma_f32_16x16x32_bf16 v[18:21], v[164:167], v[196:199], v[18:21]
	v_mfma_f32_16x16x32_bf16 v[10:13], v[172:175], v[196:199], v[10:13]
	v_mfma_f32_16x16x32_bf16 v[6:9], v[164:167], v[208:211], v[6:9]
	v_mfma_f32_16x16x32_bf16 v[2:5], v[172:175], v[208:211], v[2:5]
	v_mfma_f32_16x16x32_bf16 v[50:53], v[168:171], v[184:187], v[50:53]
	v_mfma_f32_16x16x32_bf16 v[42:45], v[176:179], v[184:187], v[42:45]
	v_mfma_f32_16x16x32_bf16 v[34:37], v[168:171], v[192:195], v[34:37]
	v_mfma_f32_16x16x32_bf16 v[26:29], v[176:179], v[192:195], v[26:29]
	v_mfma_f32_16x16x32_bf16 v[18:21], v[168:171], v[200:203], v[18:21]
	v_mfma_f32_16x16x32_bf16 v[10:13], v[176:179], v[200:203], v[10:13]
	v_mfma_f32_16x16x32_bf16 v[6:9], v[168:171], v[212:215], v[6:9]
	v_mfma_f32_16x16x32_bf16 v[2:5], v[176:179], v[212:215], v[2:5]
	s_setprio 0
	s_barrier
	s_add_i32 s83, 0, 0x18000
	v_add_u32_e32 v144, s83, v147
	s_add_i32 s84, 0, 0x1c000
	ds_read_b128 v[140:143], v144
	ds_read_b128 v[152:155], v144 offset:1024
	ds_read_b128 v[156:159], v144 offset:2048
	ds_read_b128 v[160:163], v144 offset:3072
	v_add_u32_e32 v144, s84, v147
	ds_read_b128 v[164:167], v144
	ds_read_b128 v[168:171], v144 offset:1024
	ds_read_b128 v[172:175], v144 offset:2048
	ds_read_b128 v[176:179], v144 offset:3072
	s_add_u32 s26, s62, 0x40000
	s_addc_u32 s27, s63, 0
	s_mov_b32 m0, s45
	v_lshl_add_u64 v[222:223], s[26:27], 0, v[134:135]
	ds_read_b128 v[180:183], v150 offset:32768
	ds_read_b128 v[184:187], v150 offset:33792
	ds_read_b128 v[188:191], v150 offset:34816
	ds_read_b128 v[192:195], v150 offset:35840
	ds_read_b128 v[196:199], v150 offset:36864
	ds_read_b128 v[200:203], v150 offset:37888
	ds_read_b128 v[208:211], v150 offset:38912
	ds_read_b128 v[212:215], v150 offset:39936
	global_load_lds_dwordx4 v[222:223], off
	v_lshl_add_u64 v[222:223], s[26:27], 0, v[132:133]
	s_mov_b32 m0, s64
	s_nop 0
	global_load_lds_dwordx4 v[222:223], off
	s_waitcnt vmcnt(8)
	s_waitcnt lgkmcnt(0)
	s_barrier
	s_setprio 1
	s_waitcnt lgkmcnt(0)
	v_mfma_f32_16x16x32_bf16 v[126:129], v[140:143], v[180:183], v[126:129]
	v_mfma_f32_16x16x32_bf16 v[122:125], v[156:159], v[180:183], v[122:125]
	v_mfma_f32_16x16x32_bf16 v[118:121], v[140:143], v[188:191], v[118:121]
	v_mfma_f32_16x16x32_bf16 v[110:113], v[156:159], v[188:191], v[110:113]
	v_mfma_f32_16x16x32_bf16 v[102:105], v[140:143], v[196:199], v[102:105]
	v_mfma_f32_16x16x32_bf16 v[94:97], v[156:159], v[196:199], v[94:97]
	v_mfma_f32_16x16x32_bf16 v[86:89], v[140:143], v[208:211], v[86:89]
	v_mfma_f32_16x16x32_bf16 v[78:81], v[156:159], v[208:211], v[78:81]
	v_mfma_f32_16x16x32_bf16 v[126:129], v[152:155], v[184:187], v[126:129]
	v_mfma_f32_16x16x32_bf16 v[122:125], v[160:163], v[184:187], v[122:125]
	v_mfma_f32_16x16x32_bf16 v[118:121], v[152:155], v[192:195], v[118:121]
	v_mfma_f32_16x16x32_bf16 v[110:113], v[160:163], v[192:195], v[110:113]
	v_mfma_f32_16x16x32_bf16 v[102:105], v[152:155], v[200:203], v[102:105]
	v_mfma_f32_16x16x32_bf16 v[94:97], v[160:163], v[200:203], v[94:97]
	v_mfma_f32_16x16x32_bf16 v[86:89], v[152:155], v[212:215], v[86:89]
	v_mfma_f32_16x16x32_bf16 v[78:81], v[160:163], v[212:215], v[78:81]
	s_setprio 0
	s_setprio 1
	v_mfma_f32_16x16x32_bf16 v[114:117], v[164:167], v[180:183], v[114:117]
	v_mfma_f32_16x16x32_bf16 v[106:109], v[172:175], v[180:183], v[106:109]
	v_mfma_f32_16x16x32_bf16 v[98:101], v[164:167], v[188:191], v[98:101]
	v_mfma_f32_16x16x32_bf16 v[90:93], v[172:175], v[188:191], v[90:93]
	v_mfma_f32_16x16x32_bf16 v[82:85], v[164:167], v[196:199], v[82:85]
	v_mfma_f32_16x16x32_bf16 v[74:77], v[172:175], v[196:199], v[74:77]
	v_mfma_f32_16x16x32_bf16 v[70:73], v[164:167], v[208:211], v[70:73]
	v_mfma_f32_16x16x32_bf16 v[66:69], v[172:175], v[208:211], v[66:69]
	v_mfma_f32_16x16x32_bf16 v[114:117], v[168:171], v[184:187], v[114:117]
	v_mfma_f32_16x16x32_bf16 v[106:109], v[176:179], v[184:187], v[106:109]
	v_mfma_f32_16x16x32_bf16 v[98:101], v[168:171], v[192:195], v[98:101]
	v_mfma_f32_16x16x32_bf16 v[90:93], v[176:179], v[192:195], v[90:93]
	v_mfma_f32_16x16x32_bf16 v[82:85], v[168:171], v[200:203], v[82:85]
	v_mfma_f32_16x16x32_bf16 v[74:77], v[176:179], v[200:203], v[74:77]
	v_mfma_f32_16x16x32_bf16 v[70:73], v[168:171], v[212:215], v[70:73]
	v_mfma_f32_16x16x32_bf16 v[66:69], v[176:179], v[212:215], v[66:69]
	s_setprio 0
	s_barrier
; DI unsigned cvtpk(float lo, float hi) { f32x2_t v = {lo, hi}; bf16x2_t b = __builtin_convertvector(v, bf16x2_t); return __builtin_bit_cast(unsigned, b); }
; #define PG8_STAGE(bufoff, gbase, voff) do { _Pragma("unroll") for (int _i = 0; _i < 2; ++_i) \
;         __builtin_amdgcn_global_load_lds((const unsigned*)((const char*)(gbase) + (voff)[_i]), (LAS unsigned*)(lds + (bufoff) + ldsw + _i * 8192), 16, 0, 0); } while (0)
; #define PG8_LDA(dst, b, h) do { _Pragma("unroll") for (int m = 0; m < 4; ++m) _Pragma("unroll") for (int k = 0; k < 2; ++k) dst[m][k] = *(const LAS bf16x8*)(lds + PG8_SA(b, h) + aoff + m * 2048 + k * 1024); } while (0)
; #define PG8_MMA(ai, bj, At, Bt) do { __builtin_amdgcn_s_setprio(1); _Pragma("unroll") for (int m = 0; m < 4; ++m) _Pragma("unroll") for (int n = 0; n < 2; ++n) _Pragma("unroll") for (int k = 0; k < 2; ++k) \
;         acc[ai][bj][m][n] = __builtin_amdgcn_mfma_f32_16x16x32_bf16(Bt[n][k], At[m][k], acc[ai][bj][m][n], 0, 0, 0); __builtin_amdgcn_s_setprio(0); } while (0)
;     DI void operator()(const f32x4 (&acc)[2][2][4][2], const Unit& u, int wr, int wc, int fr, int fq) const {
;         const int row0 = u.pm * BM + wr * 64 + fr, col0 = u.pn * BM + wc * 32 + 8 * fq;
;         float rs8[8]; row_rstd8(rss, row0, fr + 16 * fq, fq, rs8);
; #pragma unroll
;         for (int ai = 0; ai < 2; ++ai)
; #pragma unroll
;             for (int m = 0; m < 4; ++m) {
;                 const int row = row0 + ai * HALF + m * 16;
;                 const float rstd = rs8[ai * 4 + m];
; #pragma unroll
;                 for (int bj = 0; bj < 2; ++bj) {
;                     const f32x4 v0 = acc[ai][bj][m][0] * rstd, v1 = acc[ai][bj][m][1] * rstd;
;                     u32x4 w; w.x = cvtpk(v0[0], v0[1]); w.y = cvtpk(v0[2], v0[3]); w.z = cvtpk(v1[0], v1[1]); w.w = cvtpk(v1[2], v1[3]);
;                     *(u32x4*)(Z + (size_t)row * ldz + col0 + bj * HALF) = w;
; template <class Epi>
; DI void gemm_phase(LAS unsigned char* lds, const int tid, const Gemm g, const StaticOrder& S, const Epi& E) {
;     ...
;             PG8_LDA(At, 1, 1); PG8_STAGE(PG8_SB(1, 0), b3, voffB); PG8_STAGE(PG8_SB(1, 1), b3 + hstepB, voffB); PG8_STAGE(PG8_SA(1, 0), a3, voffA);
;             PG8_WAIT_V(8); PG8_WAIT_L(0); PG8_BAR; PG8_MMA(1, 0, At, B0); PG8_MMA(1, 1, At, B1); PG8_BAR; PG8_SCHED;
;         }
;         if (wr == 0) PG8_BAR;
;         E(acc, cur, wr, wc, fr, fq);
	s_add_i32 s26, s83, s30
	v_lshl_add_u64 v[204:205], v[204:205], 0, s[54:55]
	s_mov_b32 m0, s26
	ds_read_b128 v[180:183], v150 offset:49152
	ds_read_b128 v[184:187], v150 offset:50176
	ds_read_b128 v[188:191], v150 offset:51200
	ds_read_b128 v[192:195], v150 offset:52224
	ds_read_b128 v[196:199], v150 offset:53248
	ds_read_b128 v[200:203], v150 offset:54272
	ds_read_b128 v[208:211], v150 offset:55296
	ds_read_b128 v[212:215], v150 offset:56320
	global_load_lds_dwordx4 v[204:205], off
	s_add_i32 m0, s26, 0x2000
	s_add_u32 s26, s60, 0x40080
	v_lshl_add_u64 v[204:205], v[216:217], 0, s[54:55]
	s_addc_u32 s27, s61, 0
	s_add_i32 s60, s84, s30
	global_load_lds_dwordx4 v[204:205], off
	v_lshl_add_u64 v[204:205], s[26:27], 0, v[0:1]
	s_mov_b32 m0, s60
	s_nop 0
	global_load_lds_dwordx4 v[204:205], off
	v_lshl_add_u64 v[204:205], s[26:27], 0, v[130:131]
	s_add_i32 m0, s60, 0x2000
	s_nop 0
	global_load_lds_dwordx4 v[204:205], off
	v_lshl_add_u64 v[204:205], v[218:219], 0, s[54:55]
	s_mov_b32 m0, s66
	s_nop 0
	global_load_lds_dwordx4 v[204:205], off
	v_lshl_add_u64 v[204:205], v[220:221], 0, s[54:55]
	s_mov_b32 m0, s67
	s_nop 0
	global_load_lds_dwordx4 v[204:205], off
	s_waitcnt vmcnt(8)
	s_waitcnt lgkmcnt(0)
	s_barrier
	s_setprio 1
	s_waitcnt lgkmcnt(0)
	v_mfma_f32_16x16x32_bf16 v[62:65], v[140:143], v[180:183], v[62:65]
	v_mfma_f32_16x16x32_bf16 v[58:61], v[156:159], v[180:183], v[58:61]
	v_mfma_f32_16x16x32_bf16 v[54:57], v[140:143], v[188:191], v[54:57]
	v_mfma_f32_16x16x32_bf16 v[46:49], v[156:159], v[188:191], v[46:49]
	v_mfma_f32_16x16x32_bf16 v[38:41], v[140:143], v[196:199], v[38:41]
	v_mfma_f32_16x16x32_bf16 v[30:33], v[156:159], v[196:199], v[30:33]
	v_mfma_f32_16x16x32_bf16 v[22:25], v[140:143], v[208:211], v[22:25]
	v_mfma_f32_16x16x32_bf16 v[14:17], v[156:159], v[208:211], v[14:17]
	v_mfma_f32_16x16x32_bf16 v[62:65], v[152:155], v[184:187], v[62:65]
	v_mfma_f32_16x16x32_bf16 v[58:61], v[160:163], v[184:187], v[58:61]
	v_mfma_f32_16x16x32_bf16 v[54:57], v[152:155], v[192:195], v[54:57]
	v_mfma_f32_16x16x32_bf16 v[46:49], v[160:163], v[192:195], v[46:49]
	v_mfma_f32_16x16x32_bf16 v[38:41], v[152:155], v[200:203], v[38:41]
	v_mfma_f32_16x16x32_bf16 v[30:33], v[160:163], v[200:203], v[30:33]
	v_mfma_f32_16x16x32_bf16 v[22:25], v[152:155], v[212:215], v[22:25]
	v_mfma_f32_16x16x32_bf16 v[14:17], v[160:163], v[212:215], v[14:17]
	s_setprio 0
	s_setprio 1
	v_mfma_f32_16x16x32_bf16 v[50:53], v[164:167], v[180:183], v[50:53]
	v_mfma_f32_16x16x32_bf16 v[42:45], v[172:175], v[180:183], v[42:45]
	v_mfma_f32_16x16x32_bf16 v[34:37], v[164:167], v[188:191], v[34:37]
	v_mfma_f32_16x16x32_bf16 v[26:29], v[172:175], v[188:191], v[26:29]
	v_mfma_f32_16x16x32_bf16 v[18:21], v[164:167], v[196:199], v[18:21]
	v_mfma_f32_16x16x32_bf16 v[10:13], v[172:175], v[196:199], v[10:13]
	v_mfma_f32_16x16x32_bf16 v[6:9], v[164:167], v[208:211], v[6:9]
	v_mfma_f32_16x16x32_bf16 v[2:5], v[172:175], v[208:211], v[2:5]
	v_mfma_f32_16x16x32_bf16 v[50:53], v[168:171], v[184:187], v[50:53]
	v_mfma_f32_16x16x32_bf16 v[42:45], v[176:179], v[184:187], v[42:45]
	v_mfma_f32_16x16x32_bf16 v[34:37], v[168:171], v[192:195], v[34:37]
	v_mfma_f32_16x16x32_bf16 v[26:29], v[176:179], v[192:195], v[26:29]
	v_mfma_f32_16x16x32_bf16 v[18:21], v[168:171], v[200:203], v[18:21]
	v_mfma_f32_16x16x32_bf16 v[10:13], v[176:179], v[200:203], v[10:13]
	v_mfma_f32_16x16x32_bf16 v[6:9], v[168:171], v[212:215], v[6:9]
	v_mfma_f32_16x16x32_bf16 v[2:5], v[176:179], v[212:215], v[2:5]
	s_setprio 0
	s_barrier
	s_add_i32 s82, s82, 2
	s_add_u32 s58, s58, 0x100
	s_addc_u32 s59, s59, 0
	s_add_u32 s80, s80, 0x100
	s_addc_u32 s81, s81, 0
	s_cmp_gt_u32 s82, 13
	s_cbranch_scc0 .LBB0_420
	s_and_b64 vcc, exec, s[10:11]
	s_cbranch_vccz .LBB0_423
	s_barrier
.LBB0_423:
	s_andn2_b64 vcc, exec, s[4:5]
	s_cbranch_vccnz .Lin_noR
	v_readlane_b32 s0, v253, 49
	s_and_b32 s1, s48, 0x7f
	s_lshl_b32 s1, s1, 14
	s_nop 0
	s_add_u32 s0, s0, s1
	v_readlane_b32 s1, v253, 50
	s_nop 1
	s_addc_u32 s1, s1, 0
	s_nop 4
	global_load_dwordx4 v[228:231], v252, s[0:1]
	global_load_dwordx2 v[232:233], v252, s[0:1] offset:16
	global_load_dwordx2 v[238:239], v252, s[0:1] offset:24
.Lin_noR:
	v_lshl_add_u32 v151, s6, 8, v146
	v_lshl_or_b32 v140, s7, 8, v149
	s_mov_b32 s79, 0xff800000
	s_mov_b32 s84, 0x3a000
	s_mov_b32 s33, 0x3c000
	v_readlane_b32 s78, v254, 45
	s_mov_b32 s80, s12
	v_lshlrev_b32_e32 v143, 5, v146
	v_add_u32_e32 v143, 0x20000, v143
	ds_read_b32 v152, v143
	ds_read_b32 v154, v143 offset:4
	ds_read_b32 v156, v143 offset:8
	ds_read_b32 v160, v143 offset:16
	ds_read_b32 v144, v143 offset:24
	s_waitcnt lgkmcnt(4)
	v_pk_mul_f32 v[126:127], v[126:127], v[152:153] op_sel_hi:[1,0]
	v_pk_mul_f32 v[122:123], v[122:123], v[152:153] op_sel_hi:[1,0]
	v_ashrrev_i32_e32 v141, 31, v140
	v_pk_mul_f32 v[128:129], v[128:129], v[152:153] op_sel_hi:[1,0]
	v_pk_mul_f32 v[164:165], v[124:125], v[152:153] op_sel_hi:[1,0]
	v_cvt_pk_bf16_f32 v124, v126, v127
	v_cvt_pk_bf16_f32 v126, v122, v123
	v_mad_i64_i32 v[122:123], s[6:7], s65, v151, 0
	v_cvt_pk_bf16_f32 v125, v128, v129
	v_lshl_add_u64 v[128:129], v[122:123], 1, s[74:75]
	v_lshlrev_b64 v[122:123], 1, v[140:141]
	v_cvt_pk_bf16_f32 v127, v164, v165
	v_lshl_add_u64 v[128:129], v[128:129], 0, v[122:123]
	global_store_dwordx4 v[128:129], v[124:127], off
	v_pk_mul_f32 v[116:117], v[116:117], v[152:153] op_sel_hi:[1,0]
	v_pk_mul_f32 v[114:115], v[114:115], v[152:153] op_sel_hi:[1,0]
	v_pk_mul_f32 v[124:125], v[108:109], v[152:153] op_sel_hi:[1,0]
	v_pk_mul_f32 v[108:109], v[106:107], v[152:153] op_sel_hi:[1,0]
	v_cvt_pk_bf16_f32 v106, v114, v115
	v_cvt_pk_bf16_f32 v107, v116, v117
	v_cvt_pk_bf16_f32 v108, v108, v109
	v_cvt_pk_bf16_f32 v109, v124, v125
	global_store_dwordx4 v[128:129], v[106:109], off offset:256
	v_or_b32_e32 v114, 16, v151
	s_waitcnt lgkmcnt(3)
; DI unsigned cvtpk(float lo, float hi) { f32x2_t v = {lo, hi}; bf16x2_t b = __builtin_convertvector(v, bf16x2_t); return __builtin_bit_cast(unsigned, b); }
;     DI void operator()(const f32x4 (&acc)[2][2][4][2], const Unit& u, int wr, int wc, int fr, int fq) const {
;     ...
;         for (int ai = 0; ai < 2; ++ai)
; #pragma unroll
;             for (int m = 0; m < 4; ++m) {
;                 const int row = row0 + ai * HALF + m * 16;
;                 const float rstd = rs8[ai * 4 + m];
; #pragma unroll
;                 for (int bj = 0; bj < 2; ++bj) {
;                     const f32x4 v0 = acc[ai][bj][m][0] * rstd, v1 = acc[ai][bj][m][1] * rstd;
;                     u32x4 w; w.x = cvtpk(v0[0], v0[1]); w.y = cvtpk(v0[2], v0[3]); w.z = cvtpk(v1[0], v1[1]); w.w = cvtpk(v1[2], v1[3]);
;                     *(u32x4*)(Z + (size_t)row * ldz + col0 + bj * HALF) = w;
;                 }
	v_pk_mul_f32 v[110:111], v[110:111], v[154:155] op_sel_hi:[1,0]
	v_pk_mul_f32 v[108:109], v[120:121], v[154:155] op_sel_hi:[1,0]
	v_pk_mul_f32 v[106:107], v[118:119], v[154:155] op_sel_hi:[1,0]
	v_pk_mul_f32 v[112:113], v[112:113], v[154:155] op_sel_hi:[1,0]
	v_cvt_pk_bf16_f32 v106, v106, v107
	v_cvt_pk_bf16_f32 v107, v108, v109
	v_cvt_pk_bf16_f32 v108, v110, v111
	v_mad_i64_i32 v[110:111], s[6:7], s65, v114, 0
	v_lshl_add_u64 v[110:111], v[110:111], 1, s[74:75]
	v_cvt_pk_bf16_f32 v109, v112, v113
	v_lshl_add_u64 v[110:111], v[110:111], 0, v[122:123]
	global_store_dwordx4 v[110:111], v[106:109], off
	v_pk_mul_f32 v[100:101], v[100:101], v[154:155] op_sel_hi:[1,0]
	v_pk_mul_f32 v[98:99], v[98:99], v[154:155] op_sel_hi:[1,0]
	v_pk_mul_f32 v[106:107], v[92:93], v[154:155] op_sel_hi:[1,0]
	v_pk_mul_f32 v[92:93], v[90:91], v[154:155] op_sel_hi:[1,0]
	v_cvt_pk_bf16_f32 v90, v98, v99
	v_cvt_pk_bf16_f32 v91, v100, v101
	v_cvt_pk_bf16_f32 v92, v92, v93
	v_cvt_pk_bf16_f32 v93, v106, v107
	global_store_dwordx4 v[110:111], v[90:93], off offset:256
	v_or_b32_e32 v98, 32, v151
	s_waitcnt lgkmcnt(2)
	v_pk_mul_f32 v[94:95], v[94:95], v[156:157] op_sel_hi:[1,0]
	v_pk_mul_f32 v[92:93], v[104:105], v[156:157] op_sel_hi:[1,0]
	v_pk_mul_f32 v[90:91], v[102:103], v[156:157] op_sel_hi:[1,0]
	ds_read_b32 v158, v143 offset:12
	v_cvt_pk_bf16_f32 v90, v90, v91
	v_cvt_pk_bf16_f32 v91, v92, v93
	v_cvt_pk_bf16_f32 v92, v94, v95
	v_mad_i64_i32 v[94:95], s[6:7], s65, v98, 0
	v_pk_mul_f32 v[96:97], v[96:97], v[156:157] op_sel_hi:[1,0]
	v_lshl_add_u64 v[94:95], v[94:95], 1, s[74:75]
	v_cvt_pk_bf16_f32 v93, v96, v97
	v_lshl_add_u64 v[94:95], v[94:95], 0, v[122:123]
	global_store_dwordx4 v[94:95], v[90:93], off
	v_pk_mul_f32 v[84:85], v[84:85], v[156:157] op_sel_hi:[1,0]
	v_pk_mul_f32 v[82:83], v[82:83], v[156:157] op_sel_hi:[1,0]
	v_pk_mul_f32 v[90:91], v[76:77], v[156:157] op_sel_hi:[1,0]
	v_pk_mul_f32 v[76:77], v[74:75], v[156:157] op_sel_hi:[1,0]
	v_cvt_pk_bf16_f32 v74, v82, v83
	v_cvt_pk_bf16_f32 v75, v84, v85
	v_cvt_pk_bf16_f32 v76, v76, v77
	v_cvt_pk_bf16_f32 v77, v90, v91
	global_store_dwordx4 v[94:95], v[74:77], off offset:256
	v_or_b32_e32 v82, 48, v151
	s_waitcnt lgkmcnt(0)
	v_pk_mul_f32 v[78:79], v[78:79], v[158:159] op_sel_hi:[1,0]
	v_pk_mul_f32 v[76:77], v[88:89], v[158:159] op_sel_hi:[1,0]
	v_pk_mul_f32 v[74:75], v[86:87], v[158:159] op_sel_hi:[1,0]
	v_pk_mul_f32 v[80:81], v[80:81], v[158:159] op_sel_hi:[1,0]
	v_cvt_pk_bf16_f32 v74, v74, v75
	v_cvt_pk_bf16_f32 v75, v76, v77
	v_cvt_pk_bf16_f32 v76, v78, v79
	v_mad_i64_i32 v[78:79], s[6:7], s65, v82, 0
	v_lshl_add_u64 v[78:79], v[78:79], 1, s[74:75]
	v_cvt_pk_bf16_f32 v77, v80, v81
	v_lshl_add_u64 v[78:79], v[78:79], 0, v[122:123]
	global_store_dwordx4 v[78:79], v[74:77], off
	v_pk_mul_f32 v[72:73], v[72:73], v[158:159] op_sel_hi:[1,0]
	v_pk_mul_f32 v[70:71], v[70:71], v[158:159] op_sel_hi:[1,0]
	v_pk_mul_f32 v[74:75], v[68:69], v[158:159] op_sel_hi:[1,0]
	v_pk_mul_f32 v[68:69], v[66:67], v[158:159] op_sel_hi:[1,0]
	v_cvt_pk_bf16_f32 v66, v70, v71
	v_cvt_pk_bf16_f32 v67, v72, v73
	v_cvt_pk_bf16_f32 v68, v68, v69
	v_cvt_pk_bf16_f32 v69, v74, v75
	global_store_dwordx4 v[78:79], v[66:69], off offset:256
	v_pk_mul_f32 v[62:63], v[62:63], v[160:161] op_sel_hi:[1,0]
	ds_read_b32 v162, v143 offset:20
	v_add_u32_e32 v68, 0x80, v151
	v_pk_mul_f32 v[66:67], v[60:61], v[160:161] op_sel_hi:[1,0]
	v_pk_mul_f32 v[60:61], v[58:59], v[160:161] op_sel_hi:[1,0]
	v_cvt_pk_bf16_f32 v58, v62, v63
	v_mad_i64_i32 v[62:63], s[6:7], s65, v68, 0
	v_pk_mul_f32 v[64:65], v[64:65], v[160:161] op_sel_hi:[1,0]
	v_lshl_add_u64 v[62:63], v[62:63], 1, s[74:75]
	v_cvt_pk_bf16_f32 v59, v64, v65
	v_cvt_pk_bf16_f32 v60, v60, v61
	v_cvt_pk_bf16_f32 v61, v66, v67
	v_lshl_add_u64 v[62:63], v[62:63], 0, v[122:123]
	global_store_dwordx4 v[62:63], v[58:61], off
	v_pk_mul_f32 v[52:53], v[52:53], v[160:161] op_sel_hi:[1,0]
	v_pk_mul_f32 v[50:51], v[50:51], v[160:161] op_sel_hi:[1,0]
	v_pk_mul_f32 v[58:59], v[44:45], v[160:161] op_sel_hi:[1,0]
	v_pk_mul_f32 v[44:45], v[42:43], v[160:161] op_sel_hi:[1,0]
	v_cvt_pk_bf16_f32 v42, v50, v51
	v_cvt_pk_bf16_f32 v43, v52, v53
	v_cvt_pk_bf16_f32 v44, v44, v45
	v_cvt_pk_bf16_f32 v45, v58, v59
	global_store_dwordx4 v[62:63], v[42:45], off offset:256
	v_add_u32_e32 v50, 0x90, v151
	s_waitcnt lgkmcnt(0)
; DI unsigned cvtpk(float lo, float hi) { f32x2_t v = {lo, hi}; bf16x2_t b = __builtin_convertvector(v, bf16x2_t); return __builtin_bit_cast(unsigned, b); }
;     DI void operator()(const f32x4 (&acc)[2][2][4][2], const Unit& u, int wr, int wc, int fr, int fq) const {
;     ...
;         for (int ai = 0; ai < 2; ++ai)
; #pragma unroll
;             for (int m = 0; m < 4; ++m) {
;                 const int row = row0 + ai * HALF + m * 16;
;                 const float rstd = rs8[ai * 4 + m];
; #pragma unroll
;                 for (int bj = 0; bj < 2; ++bj) {
;                     const f32x4 v0 = acc[ai][bj][m][0] * rstd, v1 = acc[ai][bj][m][1] * rstd;
;                     u32x4 w; w.x = cvtpk(v0[0], v0[1]); w.y = cvtpk(v0[2], v0[3]); w.z = cvtpk(v1[0], v1[1]); w.w = cvtpk(v1[2], v1[3]);
;                     *(u32x4*)(Z + (size_t)row * ldz + col0 + bj * HALF) = w;
;                 }
;             }
	v_pk_mul_f32 v[46:47], v[46:47], v[162:163] op_sel_hi:[1,0]
	v_pk_mul_f32 v[44:45], v[56:57], v[162:163] op_sel_hi:[1,0]
	v_pk_mul_f32 v[42:43], v[54:55], v[162:163] op_sel_hi:[1,0]
	v_pk_mul_f32 v[48:49], v[48:49], v[162:163] op_sel_hi:[1,0]
	v_cvt_pk_bf16_f32 v42, v42, v43
	v_cvt_pk_bf16_f32 v43, v44, v45
	v_cvt_pk_bf16_f32 v44, v46, v47
	v_mad_i64_i32 v[46:47], s[6:7], s65, v50, 0
	v_lshl_add_u64 v[46:47], v[46:47], 1, s[74:75]
	v_cvt_pk_bf16_f32 v45, v48, v49
	v_lshl_add_u64 v[46:47], v[46:47], 0, v[122:123]
	global_store_dwordx4 v[46:47], v[42:45], off
	v_pk_mul_f32 v[36:37], v[36:37], v[162:163] op_sel_hi:[1,0]
	v_pk_mul_f32 v[34:35], v[34:35], v[162:163] op_sel_hi:[1,0]
	v_pk_mul_f32 v[42:43], v[28:29], v[162:163] op_sel_hi:[1,0]
	v_pk_mul_f32 v[28:29], v[26:27], v[162:163] op_sel_hi:[1,0]
	v_cvt_pk_bf16_f32 v26, v34, v35
	v_cvt_pk_bf16_f32 v27, v36, v37
	v_cvt_pk_bf16_f32 v28, v28, v29
	v_cvt_pk_bf16_f32 v29, v42, v43
	global_store_dwordx4 v[46:47], v[26:29], off offset:256
	v_add_u32_e32 v34, 0xa0, v151
	v_pk_mul_f32 v[30:31], v[30:31], v[144:145] op_sel_hi:[1,0]
	v_pk_mul_f32 v[28:29], v[40:41], v[144:145] op_sel_hi:[1,0]
	v_pk_mul_f32 v[26:27], v[38:39], v[144:145] op_sel_hi:[1,0]
	ds_read_b32 v142, v143 offset:28
	v_cvt_pk_bf16_f32 v26, v26, v27
	v_cvt_pk_bf16_f32 v27, v28, v29
	v_cvt_pk_bf16_f32 v28, v30, v31
	v_mad_i64_i32 v[30:31], s[6:7], s65, v34, 0
	v_pk_mul_f32 v[32:33], v[32:33], v[144:145] op_sel_hi:[1,0]
	v_lshl_add_u64 v[30:31], v[30:31], 1, s[74:75]
	v_cvt_pk_bf16_f32 v29, v32, v33
	v_lshl_add_u64 v[30:31], v[30:31], 0, v[122:123]
	global_store_dwordx4 v[30:31], v[26:29], off
	v_pk_mul_f32 v[20:21], v[20:21], v[144:145] op_sel_hi:[1,0]
	v_pk_mul_f32 v[18:19], v[18:19], v[144:145] op_sel_hi:[1,0]
	v_pk_mul_f32 v[26:27], v[12:13], v[144:145] op_sel_hi:[1,0]
	v_pk_mul_f32 v[12:13], v[10:11], v[144:145] op_sel_hi:[1,0]
	v_cvt_pk_bf16_f32 v10, v18, v19
	v_cvt_pk_bf16_f32 v11, v20, v21
	v_cvt_pk_bf16_f32 v12, v12, v13
	v_cvt_pk_bf16_f32 v13, v26, v27
	global_store_dwordx4 v[30:31], v[10:13], off offset:256
	v_add_u32_e32 v18, 0xb0, v151
	s_waitcnt lgkmcnt(0)
	v_pk_mul_f32 v[14:15], v[14:15], v[142:143] op_sel_hi:[1,0]
	v_pk_mul_f32 v[12:13], v[24:25], v[142:143] op_sel_hi:[1,0]
	v_pk_mul_f32 v[10:11], v[22:23], v[142:143] op_sel_hi:[1,0]
	v_pk_mul_f32 v[16:17], v[16:17], v[142:143] op_sel_hi:[1,0]
	v_cvt_pk_bf16_f32 v10, v10, v11
	v_cvt_pk_bf16_f32 v11, v12, v13
	v_cvt_pk_bf16_f32 v12, v14, v15
	v_mad_i64_i32 v[14:15], s[6:7], s65, v18, 0
	v_lshl_add_u64 v[14:15], v[14:15], 1, s[74:75]
	v_cvt_pk_bf16_f32 v13, v16, v17
	v_lshl_add_u64 v[14:15], v[14:15], 0, v[122:123]
	global_store_dwordx4 v[14:15], v[10:13], off
	v_pk_mul_f32 v[8:9], v[8:9], v[142:143] op_sel_hi:[1,0]
	v_pk_mul_f32 v[6:7], v[6:7], v[142:143] op_sel_hi:[1,0]
	v_pk_mul_f32 v[10:11], v[4:5], v[142:143] op_sel_hi:[1,0]
	v_pk_mul_f32 v[4:5], v[2:3], v[142:143] op_sel_hi:[1,0]
	v_cvt_pk_bf16_f32 v2, v6, v7
	v_cvt_pk_bf16_f32 v3, v8, v9
	v_cvt_pk_bf16_f32 v4, v4, v5
	v_cvt_pk_bf16_f32 v5, v10, v11
	s_mov_b64 s[6:7], -1
	s_andn2_b64 vcc, exec, s[4:5]
	global_store_dwordx4 v[14:15], v[2:5], off offset:256
	s_cbranch_vccnz .LBB0_416
	s_andn2_b64 vcc, exec, s[8:9]
	s_cbranch_vccnz .LBB0_415
	s_barrier
	s_branch .LBB0_415
